# EpiResid epilogues de-serialised (batched hin loads, counted vmcnt) + hgrn_post 8-way pipelining + attention max3/fast path
# speedup vs baseline: 1.0217x; 1.0131x over previous
;     __device__ __forceinline__ void operator()(const f32x4 (&acc)[2][2][4][2], const Unit& u, int wr, int wc, int fr, int fq) const {
;         const int row0 = u.pm * 256 + wr * 64 + fr, col0 = u.pn * 256 + wc * 32 + 4 * fq, b = u.pm >> 3;
;         f32x4 gv[2][2];
; #pragma unroll
;         for (int bj = 0; bj < 2; ++bj)
; #pragma unroll
;             for (int n = 0; n < 2; ++n) gv[bj][n] = *(const f32x4*)(gate + (size_t)b * MODW + col0 + bj * 128 + n * 16) * scale;
; #pragma unroll
;         for (int ai = 0; ai < 2; ++ai)
; #pragma unroll
;             for (int m = 0; m < 4; ++m) { const size_t off = (size_t)(row0 + ai * 128 + m * 16) * D + col0;
; #pragma unroll
;                 for (int bj = 0; bj < 2; ++bj)
; #pragma unroll
;                     for (int n = 0; n < 2; ++n) { const f32x4 hv = *(const f32x4*)(hin + off + bj * 128 + n * 16);
;                         *(f32x4*)(hout + off + bj * 128 + n * 16) = hv + gv[bj][n] * acc[ai][bj][m][n]; } }
;     }
.LBB0_412:
	s_ashr_i32 s4, s39, 3
	s_mul_hi_i32 s5, s4, 0x12000
	s_mul_i32 s4, s4, 0x12000
	s_add_u32 s4, s30, s4
	s_addc_u32 s5, s31, s5
	v_lshl_or_b32 v158, s40, 8, v161
	v_lshlrev_b32_e32 v159, 2, v158
	global_load_dwordx4 v[138:141], v159, s[4:5]
	global_load_dwordx4 v[142:145], v159, s[4:5] offset:64
	global_load_dwordx4 v[146:149], v159, s[4:5] offset:512
	global_load_dwordx4 v[150:153], v159, s[4:5] offset:576
	v_lshl_add_u32 v172, s39, 8, v1
	v_lshlrev_b32_e32 v173, 13, v172
	v_add_u32_e32 v173, v173, v159
	v_mov_b32_e32 v210, v173
	global_load_dwordx4 v[154:157], v210, s[12:13]
	global_load_dwordx4 v[164:167], v210, s[12:13] offset:64
	global_load_dwordx4 v[168:171], v210, s[12:13] offset:512
	global_load_dwordx4 v[186:189], v210, s[12:13] offset:576
	v_add_u32_e32 v211, 0x20000, v173
	global_load_dwordx4 v[190:193], v211, s[12:13]
	global_load_dwordx4 v[194:197], v211, s[12:13] offset:64
	global_load_dwordx4 v[198:201], v211, s[12:13] offset:512
	global_load_dwordx4 v[202:205], v211, s[12:13] offset:576
	v_add_u32_e32 v214, 0x40000, v173
	global_load_dwordx4 v[206:209], v214, s[12:13]
	global_load_dwordx4 v[236:239], v214, s[12:13] offset:64
	global_load_dwordx4 v[240:243], v214, s[12:13] offset:512
	global_load_dwordx4 v[244:247], v214, s[12:13] offset:576
	s_ashr_i32 s4, s39, 3
	s_mul_hi_i32 s5, s4, 0x12000
	s_mul_i32 s4, s4, 0x12000
	s_add_u32 s4, s30, s4
	s_addc_u32 s5, s31, s5
	s_mov_b64 s[4:5], 0x100000
	s_and_b64 vcc, exec, s[8:9]
	s_mov_b64 s[4:5], 0x120000
	s_mov_b64 s[4:5], 0x140000
	s_mov_b64 s[4:5], 0x160000
	s_mov_b64 s[4:5], -1
	s_waitcnt vmcnt(12)
	v_pk_mul_f32 v[140:141], v[140:141], 0.5 op_sel_hi:[1,0]
	v_pk_mul_f32 v[138:139], v[138:139], 0.5 op_sel_hi:[1,0]
	v_pk_mul_f32 v[144:145], v[144:145], 0.5 op_sel_hi:[1,0]
	v_pk_mul_f32 v[142:143], v[142:143], 0.5 op_sel_hi:[1,0]
	v_pk_mul_f32 v[148:149], v[148:149], 0.5 op_sel_hi:[1,0]
	v_pk_mul_f32 v[146:147], v[146:147], 0.5 op_sel_hi:[1,0]
	v_pk_mul_f32 v[152:153], v[152:153], 0.5 op_sel_hi:[1,0]
	v_pk_mul_f32 v[150:151], v[150:151], 0.5 op_sel_hi:[1,0]
	s_waitcnt vmcnt(8)
	v_pk_fma_f32 v[130:131], v[130:131], v[140:141], v[156:157]
	v_pk_fma_f32 v[128:129], v[128:129], v[138:139], v[154:155]
	v_pk_fma_f32 v[126:127], v[126:127], v[144:145], v[166:167]
	v_pk_fma_f32 v[124:125], v[124:125], v[142:143], v[164:165]
	v_pk_fma_f32 v[122:123], v[122:123], v[148:149], v[170:171]
	v_pk_fma_f32 v[120:121], v[120:121], v[146:147], v[168:169]
	v_pk_fma_f32 v[118:119], v[118:119], v[152:153], v[188:189]
	v_pk_fma_f32 v[116:117], v[116:117], v[150:151], v[186:187]
	global_store_dwordx4 v210, v[128:131], s[54:55]
	global_store_dwordx4 v210, v[124:127], s[54:55] offset:64
	global_store_dwordx4 v210, v[120:123], s[54:55] offset:512
	global_store_dwordx4 v210, v[116:119], s[54:55] offset:576
	v_add_u32_e32 v210, 0x60000, v173
	global_load_dwordx4 v[154:157], v210, s[12:13]
	global_load_dwordx4 v[164:167], v210, s[12:13] offset:64
	global_load_dwordx4 v[168:171], v210, s[12:13] offset:512
	global_load_dwordx4 v[186:189], v210, s[12:13] offset:576
	s_waitcnt vmcnt(12)
	v_pk_fma_f32 v[114:115], v[114:115], v[140:141], v[192:193]
	v_pk_fma_f32 v[112:113], v[112:113], v[138:139], v[190:191]
	v_pk_fma_f32 v[110:111], v[110:111], v[144:145], v[196:197]
	v_pk_fma_f32 v[108:109], v[108:109], v[142:143], v[194:195]
	v_pk_fma_f32 v[106:107], v[106:107], v[148:149], v[200:201]
	v_pk_fma_f32 v[104:105], v[104:105], v[146:147], v[198:199]
	v_pk_fma_f32 v[102:103], v[102:103], v[152:153], v[204:205]
	v_pk_fma_f32 v[100:101], v[100:101], v[150:151], v[202:203]
	global_store_dwordx4 v211, v[112:115], s[54:55]
	global_store_dwordx4 v211, v[108:111], s[54:55] offset:64
	global_store_dwordx4 v211, v[104:107], s[54:55] offset:512
	global_store_dwordx4 v211, v[100:103], s[54:55] offset:576
	v_add_u32_e32 v211, 0x100000, v173
	global_load_dwordx4 v[190:193], v211, s[12:13]
	global_load_dwordx4 v[194:197], v211, s[12:13] offset:64
	global_load_dwordx4 v[198:201], v211, s[12:13] offset:512
	global_load_dwordx4 v[202:205], v211, s[12:13] offset:576
	s_waitcnt vmcnt(16)
	v_pk_fma_f32 v[98:99], v[98:99], v[140:141], v[208:209]
	v_pk_fma_f32 v[96:97], v[96:97], v[138:139], v[206:207]
	v_pk_fma_f32 v[94:95], v[94:95], v[144:145], v[238:239]
	v_pk_fma_f32 v[92:93], v[92:93], v[142:143], v[236:237]
	v_pk_fma_f32 v[90:91], v[90:91], v[148:149], v[242:243]
	v_pk_fma_f32 v[88:89], v[88:89], v[146:147], v[240:241]
	v_pk_fma_f32 v[86:87], v[86:87], v[152:153], v[246:247]
	v_pk_fma_f32 v[84:85], v[84:85], v[150:151], v[244:245]
	global_store_dwordx4 v214, v[96:99], s[54:55]
	global_store_dwordx4 v214, v[92:95], s[54:55] offset:64
	global_store_dwordx4 v214, v[88:91], s[54:55] offset:512
	global_store_dwordx4 v214, v[84:87], s[54:55] offset:576
	v_add_u32_e32 v214, 0x120000, v173
	global_load_dwordx4 v[206:209], v214, s[12:13]
	global_load_dwordx4 v[236:239], v214, s[12:13] offset:64
	global_load_dwordx4 v[240:243], v214, s[12:13] offset:512
	global_load_dwordx4 v[244:247], v214, s[12:13] offset:576
	s_waitcnt vmcnt(16)
;     __device__ __forceinline__ void operator()(const f32x4 (&acc)[2][2][4][2], const Unit& u, int wr, int wc, int fr, int fq) const {
;     ...
;         for (int ai = 0; ai < 2; ++ai)
; #pragma unroll
;             for (int m = 0; m < 4; ++m) { const size_t off = (size_t)(row0 + ai * 128 + m * 16) * D + col0;
; #pragma unroll
;                 for (int bj = 0; bj < 2; ++bj)
; #pragma unroll
;                     for (int n = 0; n < 2; ++n) { const f32x4 hv = *(const f32x4*)(hin + off + bj * 128 + n * 16);
;                         *(f32x4*)(hout + off + bj * 128 + n * 16) = hv + gv[bj][n] * acc[ai][bj][m][n]; } }
;     }
	v_pk_fma_f32 v[82:83], v[82:83], v[140:141], v[156:157]
	v_pk_fma_f32 v[80:81], v[80:81], v[138:139], v[154:155]
	v_pk_fma_f32 v[78:79], v[78:79], v[144:145], v[166:167]
	v_pk_fma_f32 v[76:77], v[76:77], v[142:143], v[164:165]
	v_pk_fma_f32 v[74:75], v[74:75], v[148:149], v[170:171]
	v_pk_fma_f32 v[72:73], v[72:73], v[146:147], v[168:169]
	v_pk_fma_f32 v[70:71], v[70:71], v[152:153], v[188:189]
	v_pk_fma_f32 v[68:69], v[68:69], v[150:151], v[186:187]
	global_store_dwordx4 v210, v[80:83], s[54:55]
	global_store_dwordx4 v210, v[76:79], s[54:55] offset:64
	global_store_dwordx4 v210, v[72:75], s[54:55] offset:512
	global_store_dwordx4 v210, v[68:71], s[54:55] offset:576
	v_add_u32_e32 v210, 0x140000, v173
	global_load_dwordx4 v[154:157], v210, s[12:13]
	global_load_dwordx4 v[164:167], v210, s[12:13] offset:64
	global_load_dwordx4 v[168:171], v210, s[12:13] offset:512
	global_load_dwordx4 v[186:189], v210, s[12:13] offset:576
	s_waitcnt vmcnt(16)
	v_pk_fma_f32 v[66:67], v[66:67], v[140:141], v[192:193]
	v_pk_fma_f32 v[64:65], v[64:65], v[138:139], v[190:191]
	v_pk_fma_f32 v[62:63], v[62:63], v[144:145], v[196:197]
	v_pk_fma_f32 v[60:61], v[60:61], v[142:143], v[194:195]
	v_pk_fma_f32 v[58:59], v[58:59], v[148:149], v[200:201]
	v_pk_fma_f32 v[56:57], v[56:57], v[146:147], v[198:199]
	v_pk_fma_f32 v[54:55], v[54:55], v[152:153], v[204:205]
	v_pk_fma_f32 v[52:53], v[52:53], v[150:151], v[202:203]
	global_store_dwordx4 v211, v[64:67], s[54:55]
	global_store_dwordx4 v211, v[60:63], s[54:55] offset:64
	global_store_dwordx4 v211, v[56:59], s[54:55] offset:512
	global_store_dwordx4 v211, v[52:55], s[54:55] offset:576
	v_add_u32_e32 v211, 0x160000, v173
	global_load_dwordx4 v[190:193], v211, s[12:13]
	global_load_dwordx4 v[194:197], v211, s[12:13] offset:64
	global_load_dwordx4 v[198:201], v211, s[12:13] offset:512
	global_load_dwordx4 v[202:205], v211, s[12:13] offset:576
	s_waitcnt vmcnt(16)
	v_pk_fma_f32 v[50:51], v[50:51], v[140:141], v[208:209]
	v_pk_fma_f32 v[48:49], v[48:49], v[138:139], v[206:207]
	v_pk_fma_f32 v[46:47], v[46:47], v[144:145], v[238:239]
	v_pk_fma_f32 v[44:45], v[44:45], v[142:143], v[236:237]
	v_pk_fma_f32 v[42:43], v[42:43], v[148:149], v[242:243]
	v_pk_fma_f32 v[40:41], v[40:41], v[146:147], v[240:241]
	v_pk_fma_f32 v[38:39], v[38:39], v[152:153], v[246:247]
	v_pk_fma_f32 v[36:37], v[36:37], v[150:151], v[244:245]
	global_store_dwordx4 v214, v[48:51], s[54:55]
	global_store_dwordx4 v214, v[44:47], s[54:55] offset:64
	global_store_dwordx4 v214, v[40:43], s[54:55] offset:512
	global_store_dwordx4 v214, v[36:39], s[54:55] offset:576
	s_waitcnt vmcnt(12)
	v_pk_fma_f32 v[34:35], v[34:35], v[140:141], v[156:157]
	v_pk_fma_f32 v[32:33], v[32:33], v[138:139], v[154:155]
	v_pk_fma_f32 v[30:31], v[30:31], v[144:145], v[166:167]
	v_pk_fma_f32 v[28:29], v[28:29], v[142:143], v[164:165]
	v_pk_fma_f32 v[26:27], v[26:27], v[148:149], v[170:171]
	v_pk_fma_f32 v[24:25], v[24:25], v[146:147], v[168:169]
	v_pk_fma_f32 v[22:23], v[22:23], v[152:153], v[188:189]
	v_pk_fma_f32 v[20:21], v[20:21], v[150:151], v[186:187]
	global_store_dwordx4 v210, v[32:35], s[54:55]
	global_store_dwordx4 v210, v[28:31], s[54:55] offset:64
	global_store_dwordx4 v210, v[24:27], s[54:55] offset:512
	global_store_dwordx4 v210, v[20:23], s[54:55] offset:576
	s_waitcnt vmcnt(8)
	v_pk_fma_f32 v[18:19], v[18:19], v[140:141], v[192:193]
	v_pk_fma_f32 v[16:17], v[16:17], v[138:139], v[190:191]
	v_pk_fma_f32 v[14:15], v[14:15], v[144:145], v[196:197]
	v_pk_fma_f32 v[12:13], v[12:13], v[142:143], v[194:195]
	v_pk_fma_f32 v[10:11], v[10:11], v[148:149], v[200:201]
	v_pk_fma_f32 v[8:9], v[8:9], v[146:147], v[198:199]
	v_pk_fma_f32 v[6:7], v[6:7], v[152:153], v[204:205]
	v_pk_fma_f32 v[4:5], v[4:5], v[150:151], v[202:203]
	global_store_dwordx4 v211, v[16:19], s[54:55]
	global_store_dwordx4 v211, v[12:15], s[54:55] offset:64
	global_store_dwordx4 v211, v[8:11], s[54:55] offset:512
	global_store_dwordx4 v211, v[4:7], s[54:55] offset:576
	s_cbranch_vccnz .LBB0_397
	s_andn2_b64 vcc, exec, s[14:15]
	s_cbranch_vccnz .LBB0_396
	s_barrier
	s_branch .LBB0_396

; __device__ __forceinline__ void hgrn_post_phase(const float* oraw, const bf16* z, const float* onorm, bf16* oa, int gw, int NGW, int lane) {
;     const float g0 = onorm[2 * lane], g1 = onorm[2 * lane + 1];
;     for (int it = gw; it < M * 4; it += NGW) {
;         const int row = it >> 2, h = it & 3;
;         const float2 o = *(const float2*)(oraw + (size_t)row * 512 + h * 128 + 2 * lane);
;         const float r = rsqrtf(wave_sum(o.x * o.x + o.y * o.y) * (1.0f / 128.0f) + EPS);
;         const unsigned gw2 = *(const unsigned*)(z + (size_t)row * ZP + C_HG + h * 128 + 2 * lane);
.LBB0_792:
	s_or_b64 exec, exec, s[4:5]
	v_mov_b32_e32 v1, v0
	s_waitcnt lgkmcnt(0)
	s_barrier
	s_nop 0
	v_readfirstlane_b32 s0, v1
	s_ashr_i32 s1, s0, 6
	s_add_i32 s0, s1, s47
	s_cmp_gt_i32 s0, 0xffff
	s_cbranch_scc1 .LBB0_795
	s_load_dwordx2 s[4:5], s[56:57], 0x58
	s_lshl_b32 s68, s58, 7
	v_lshlrev_b32_e32 v1, 1, v1
	s_lshl_b64 s[6:7], s[68:69], 2
	v_and_b32_e32 v2, 0x7e, v1
	s_waitcnt lgkmcnt(0)
	s_add_u32 s4, s4, s6
	s_addc_u32 s5, s5, s7
	v_lshlrev_b32_e32 v1, 2, v2
	global_load_dwordx2 v[4:5], v1, s[4:5]
	v_cmp_lt_i32_e32 vcc, v219, v218
	s_lshl_b32 s1, s1, 7
	v_readlane_b32 s4, v255, 10
	v_cndmask_b32_e32 v1, v217, v219, vcc
	v_cmp_lt_i32_e32 vcc, v220, v218
	v_readlane_b32 s15, v255, 11
	v_lshlrev_b32_e32 v1, 2, v1
	v_cndmask_b32_e32 v6, v217, v220, vcc
	v_cmp_lt_i32_e32 vcc, v221, v218
	v_lshlrev_b32_e32 v6, 2, v6
	s_add_i32 s1, s4, s1
	v_cndmask_b32_e32 v7, v217, v221, vcc
	v_cmp_lt_i32_e32 vcc, v222, v218
	v_lshlrev_b32_e32 v7, 2, v7
	v_readlane_b32 s12, v252, 24
	v_cndmask_b32_e32 v8, v217, v222, vcc
	v_cmp_lt_i32_e32 vcc, v235, v218
	v_lshlrev_b32_e32 v8, 2, v8
	v_readlane_b32 s13, v252, 37
	v_cndmask_b32_e32 v9, v217, v235, vcc
	v_cmp_lt_i32_e32 vcc, v224, v218
	v_lshlrev_b32_e32 v9, 2, v9
	v_readlane_b32 s14, v252, 38
	v_cndmask_b32_e32 v10, v217, v224, vcc
	v_lshlrev_b32_e32 v10, 2, v10
	v_lshlrev_b32_e32 v100, 2, v2
	v_lshlrev_b32_e32 v101, 1, v2
.Lhp_check:
	s_mul_i32 s16, s12, 7
	s_add_i32 s16, s16, s0
	s_cmp_gt_i32 s16, 0xffff
	s_cbranch_scc1 .Lhp_tail
	s_mov_b32 s16, s0
	s_mov_b32 s17, s1
	s_ashr_i32 s4, s16, 2
	s_ashr_i32 s5, s4, 31
	s_lshl_b64 s[6:7], s[4:5], 11
	s_add_u32 s6, s13, s6
	s_addc_u32 s7, s14, s7
	s_and_b32 s8, s17, 0x180
	s_lshl_b32 s9, s8, 2
	s_add_u32 s6, s6, s9
	s_addc_u32 s7, s7, 0
	s_mul_i32 s10, s4, 0x5a00
	s_mul_hi_i32 s9, s4, 0x5a00
	s_add_u32 s10, s76, s10
	s_addc_u32 s9, s77, s9
	s_lshl_b32 s8, s8, 1
	s_add_u32 s10, s10, s8
	s_addc_u32 s11, s9, 0
	global_load_dword v121, v101, s[10:11] offset:3072
	global_load_dwordx2 v[104:105], v100, s[6:7]
	s_add_i32 s16, s16, s12
	s_add_i32 s17, s17, s15
	s_ashr_i32 s4, s16, 2
	s_ashr_i32 s5, s4, 31
	s_lshl_b64 s[6:7], s[4:5], 11
	s_add_u32 s6, s13, s6
	s_addc_u32 s7, s14, s7
	s_and_b32 s8, s17, 0x180
	s_lshl_b32 s9, s8, 2
	s_add_u32 s6, s6, s9
	s_addc_u32 s7, s7, 0
	s_mul_i32 s10, s4, 0x5a00
	s_mul_hi_i32 s9, s4, 0x5a00
	s_add_u32 s10, s76, s10
	s_addc_u32 s9, s77, s9
	s_lshl_b32 s8, s8, 1
	s_add_u32 s10, s10, s8
	s_addc_u32 s11, s9, 0
	global_load_dword v122, v101, s[10:11] offset:3072
	global_load_dwordx2 v[106:107], v100, s[6:7]
	s_add_i32 s16, s16, s12
	s_add_i32 s17, s17, s15
	s_ashr_i32 s4, s16, 2
	s_ashr_i32 s5, s4, 31
	s_lshl_b64 s[6:7], s[4:5], 11
	s_add_u32 s6, s13, s6
	s_addc_u32 s7, s14, s7
	s_and_b32 s8, s17, 0x180
	s_lshl_b32 s9, s8, 2
	s_add_u32 s6, s6, s9
	s_addc_u32 s7, s7, 0
	s_mul_i32 s10, s4, 0x5a00
	s_mul_hi_i32 s9, s4, 0x5a00
	s_add_u32 s10, s76, s10
	s_addc_u32 s9, s77, s9
	s_lshl_b32 s8, s8, 1
	s_add_u32 s10, s10, s8
	s_addc_u32 s11, s9, 0
	global_load_dword v123, v101, s[10:11] offset:3072
	global_load_dwordx2 v[108:109], v100, s[6:7]
	s_add_i32 s16, s16, s12
	s_add_i32 s17, s17, s15
	s_ashr_i32 s4, s16, 2
	s_ashr_i32 s5, s4, 31
	s_lshl_b64 s[6:7], s[4:5], 11
	s_add_u32 s6, s13, s6
	s_addc_u32 s7, s14, s7
	s_and_b32 s8, s17, 0x180
	s_lshl_b32 s9, s8, 2
	s_add_u32 s6, s6, s9
	s_addc_u32 s7, s7, 0
	s_mul_i32 s10, s4, 0x5a00
	s_mul_hi_i32 s9, s4, 0x5a00
	s_add_u32 s10, s76, s10
	s_addc_u32 s9, s77, s9
	s_lshl_b32 s8, s8, 1
	s_add_u32 s10, s10, s8
	s_addc_u32 s11, s9, 0
	global_load_dword v124, v101, s[10:11] offset:3072
	global_load_dwordx2 v[110:111], v100, s[6:7]
	s_add_i32 s16, s16, s12
	s_add_i32 s17, s17, s15
	s_ashr_i32 s4, s16, 2
	s_ashr_i32 s5, s4, 31
	s_lshl_b64 s[6:7], s[4:5], 11
	s_add_u32 s6, s13, s6
	s_addc_u32 s7, s14, s7
	s_and_b32 s8, s17, 0x180
	s_lshl_b32 s9, s8, 2
	s_add_u32 s6, s6, s9
	s_addc_u32 s7, s7, 0
	s_mul_i32 s10, s4, 0x5a00
	s_mul_hi_i32 s9, s4, 0x5a00
	s_add_u32 s10, s76, s10
	s_addc_u32 s9, s77, s9
	s_lshl_b32 s8, s8, 1
	s_add_u32 s10, s10, s8
	s_addc_u32 s11, s9, 0
	global_load_dword v125, v101, s[10:11] offset:3072
	global_load_dwordx2 v[112:113], v100, s[6:7]
	s_add_i32 s16, s16, s12
	s_add_i32 s17, s17, s15
	s_ashr_i32 s4, s16, 2
	s_ashr_i32 s5, s4, 31
	s_lshl_b64 s[6:7], s[4:5], 11
	s_add_u32 s6, s13, s6
	s_addc_u32 s7, s14, s7
	s_and_b32 s8, s17, 0x180
	s_lshl_b32 s9, s8, 2
	s_add_u32 s6, s6, s9
	s_addc_u32 s7, s7, 0
	s_mul_i32 s10, s4, 0x5a00
	s_mul_hi_i32 s9, s4, 0x5a00
	s_add_u32 s10, s76, s10
	s_addc_u32 s9, s77, s9
	s_lshl_b32 s8, s8, 1
	s_add_u32 s10, s10, s8
	s_addc_u32 s11, s9, 0
	global_load_dword v126, v101, s[10:11] offset:3072
	global_load_dwordx2 v[114:115], v100, s[6:7]
	s_add_i32 s16, s16, s12
	s_add_i32 s17, s17, s15
	s_ashr_i32 s4, s16, 2
	s_ashr_i32 s5, s4, 31
	s_lshl_b64 s[6:7], s[4:5], 11
	s_add_u32 s6, s13, s6
	s_addc_u32 s7, s14, s7
	s_and_b32 s8, s17, 0x180
	s_lshl_b32 s9, s8, 2
	s_add_u32 s6, s6, s9
	s_addc_u32 s7, s7, 0
	s_mul_i32 s10, s4, 0x5a00
	s_mul_hi_i32 s9, s4, 0x5a00
	s_add_u32 s10, s76, s10
	s_addc_u32 s9, s77, s9
	s_lshl_b32 s8, s8, 1
	s_add_u32 s10, s10, s8
	s_addc_u32 s11, s9, 0
	global_load_dword v127, v101, s[10:11] offset:3072
	global_load_dwordx2 v[116:117], v100, s[6:7]
	s_add_i32 s16, s16, s12
	s_add_i32 s17, s17, s15
	s_ashr_i32 s4, s16, 2
	s_ashr_i32 s5, s4, 31
	s_lshl_b64 s[6:7], s[4:5], 11
	s_add_u32 s6, s13, s6
	s_addc_u32 s7, s14, s7
	s_and_b32 s8, s17, 0x180
	s_lshl_b32 s9, s8, 2
	s_add_u32 s6, s6, s9
	s_addc_u32 s7, s7, 0
	s_mul_i32 s10, s4, 0x5a00
	s_mul_hi_i32 s9, s4, 0x5a00
	s_add_u32 s10, s76, s10
	s_addc_u32 s9, s77, s9
	s_lshl_b32 s8, s8, 1
	s_add_u32 s10, s10, s8
	s_addc_u32 s11, s9, 0
	global_load_dword v128, v101, s[10:11] offset:3072
	global_load_dwordx2 v[118:119], v100, s[6:7]
	s_add_i32 s16, s16, s12
	s_add_i32 s17, s17, s15
	s_waitcnt vmcnt(14)
; __device__ __forceinline__ float wave_sum(float v) {
; #pragma unroll
;     for (int o = 1; o < 64; o <<= 1) v += __shfl_xor(v, o);
;     return v;
; }
; __device__ __forceinline__ void hgrn_post_phase(const float* oraw, const bf16* z, const float* onorm, bf16* oa, int gw, int NGW, int lane) {
;     ...
;         const float r = rsqrtf(wave_sum(o.x * o.x + o.y * o.y) * (1.0f / 128.0f) + EPS);
	v_pk_mul_f32 v[16:17], v[104:105], v[104:105]
	v_add_f32_e32 v129, v16, v17
	s_waitcnt vmcnt(12)
	v_pk_mul_f32 v[16:17], v[106:107], v[106:107]
	v_add_f32_e32 v130, v16, v17
	s_waitcnt vmcnt(10)
	v_pk_mul_f32 v[16:17], v[108:109], v[108:109]
	v_add_f32_e32 v131, v16, v17
	s_waitcnt vmcnt(8)
	v_pk_mul_f32 v[16:17], v[110:111], v[110:111]
	v_add_f32_e32 v132, v16, v17
	s_waitcnt vmcnt(6)
	v_pk_mul_f32 v[16:17], v[112:113], v[112:113]
	v_add_f32_e32 v133, v16, v17
	s_waitcnt vmcnt(4)
	v_pk_mul_f32 v[16:17], v[114:115], v[114:115]
	v_add_f32_e32 v134, v16, v17
	s_waitcnt vmcnt(2)
	v_pk_mul_f32 v[16:17], v[116:117], v[116:117]
	v_add_f32_e32 v135, v16, v17
	s_waitcnt vmcnt(0)
	v_pk_mul_f32 v[16:17], v[118:119], v[118:119]
	v_add_f32_e32 v136, v16, v17
	ds_bpermute_b32 v137, v1, v129
	ds_bpermute_b32 v138, v1, v130
	ds_bpermute_b32 v139, v1, v131
	ds_bpermute_b32 v140, v1, v132
	ds_bpermute_b32 v141, v1, v133
	ds_bpermute_b32 v142, v1, v134
	ds_bpermute_b32 v143, v1, v135
	ds_bpermute_b32 v144, v1, v136
	s_waitcnt lgkmcnt(7)
	v_add_f32_e32 v129, v129, v137
	s_waitcnt lgkmcnt(6)
	v_add_f32_e32 v130, v130, v138
	s_waitcnt lgkmcnt(5)
	v_add_f32_e32 v131, v131, v139
	s_waitcnt lgkmcnt(4)
	v_add_f32_e32 v132, v132, v140
	s_waitcnt lgkmcnt(3)
	v_add_f32_e32 v133, v133, v141
	s_waitcnt lgkmcnt(2)
	v_add_f32_e32 v134, v134, v142
	s_waitcnt lgkmcnt(1)
	v_add_f32_e32 v135, v135, v143
	s_waitcnt lgkmcnt(0)
	v_add_f32_e32 v136, v136, v144
	ds_bpermute_b32 v137, v6, v129
	ds_bpermute_b32 v138, v6, v130
	ds_bpermute_b32 v139, v6, v131
	ds_bpermute_b32 v140, v6, v132
	ds_bpermute_b32 v141, v6, v133
	ds_bpermute_b32 v142, v6, v134
	ds_bpermute_b32 v143, v6, v135
	ds_bpermute_b32 v144, v6, v136
	s_waitcnt lgkmcnt(7)
	v_add_f32_e32 v129, v129, v137
	s_waitcnt lgkmcnt(6)
	v_add_f32_e32 v130, v130, v138
	s_waitcnt lgkmcnt(5)
	v_add_f32_e32 v131, v131, v139
	s_waitcnt lgkmcnt(4)
	v_add_f32_e32 v132, v132, v140
	s_waitcnt lgkmcnt(3)
	v_add_f32_e32 v133, v133, v141
	s_waitcnt lgkmcnt(2)
	v_add_f32_e32 v134, v134, v142
	s_waitcnt lgkmcnt(1)
	v_add_f32_e32 v135, v135, v143
	s_waitcnt lgkmcnt(0)
	v_add_f32_e32 v136, v136, v144
	ds_bpermute_b32 v137, v7, v129
	ds_bpermute_b32 v138, v7, v130
	ds_bpermute_b32 v139, v7, v131
	ds_bpermute_b32 v140, v7, v132
	ds_bpermute_b32 v141, v7, v133
	ds_bpermute_b32 v142, v7, v134
	ds_bpermute_b32 v143, v7, v135
	ds_bpermute_b32 v144, v7, v136
	s_waitcnt lgkmcnt(7)
	v_add_f32_e32 v129, v129, v137
	s_waitcnt lgkmcnt(6)
	v_add_f32_e32 v130, v130, v138
	s_waitcnt lgkmcnt(5)
	v_add_f32_e32 v131, v131, v139
	s_waitcnt lgkmcnt(4)
	v_add_f32_e32 v132, v132, v140
	s_waitcnt lgkmcnt(3)
	v_add_f32_e32 v133, v133, v141
	s_waitcnt lgkmcnt(2)
	v_add_f32_e32 v134, v134, v142
	s_waitcnt lgkmcnt(1)
	v_add_f32_e32 v135, v135, v143
	s_waitcnt lgkmcnt(0)
	v_add_f32_e32 v136, v136, v144
	ds_bpermute_b32 v137, v8, v129
	ds_bpermute_b32 v138, v8, v130
	ds_bpermute_b32 v139, v8, v131
	ds_bpermute_b32 v140, v8, v132
	ds_bpermute_b32 v141, v8, v133
	ds_bpermute_b32 v142, v8, v134
	ds_bpermute_b32 v143, v8, v135
	ds_bpermute_b32 v144, v8, v136
	s_waitcnt lgkmcnt(7)
	v_add_f32_e32 v129, v129, v137
	s_waitcnt lgkmcnt(6)
	v_add_f32_e32 v130, v130, v138
	s_waitcnt lgkmcnt(5)
	v_add_f32_e32 v131, v131, v139
	s_waitcnt lgkmcnt(4)
	v_add_f32_e32 v132, v132, v140
	s_waitcnt lgkmcnt(3)
	v_add_f32_e32 v133, v133, v141
	s_waitcnt lgkmcnt(2)
	v_add_f32_e32 v134, v134, v142
	s_waitcnt lgkmcnt(1)
	v_add_f32_e32 v135, v135, v143
	s_waitcnt lgkmcnt(0)
	v_add_f32_e32 v136, v136, v144
	ds_bpermute_b32 v137, v9, v129
	ds_bpermute_b32 v138, v9, v130
	ds_bpermute_b32 v139, v9, v131
	ds_bpermute_b32 v140, v9, v132
	ds_bpermute_b32 v141, v9, v133
	ds_bpermute_b32 v142, v9, v134
	ds_bpermute_b32 v143, v9, v135
	ds_bpermute_b32 v144, v9, v136
	s_waitcnt lgkmcnt(7)
	v_add_f32_e32 v129, v129, v137
	s_waitcnt lgkmcnt(6)
	v_add_f32_e32 v130, v130, v138
	s_waitcnt lgkmcnt(5)
	v_add_f32_e32 v131, v131, v139
	s_waitcnt lgkmcnt(4)
	v_add_f32_e32 v132, v132, v140
	s_waitcnt lgkmcnt(3)
	v_add_f32_e32 v133, v133, v141
	s_waitcnt lgkmcnt(2)
	v_add_f32_e32 v134, v134, v142
	s_waitcnt lgkmcnt(1)
	v_add_f32_e32 v135, v135, v143
	s_waitcnt lgkmcnt(0)
	v_add_f32_e32 v136, v136, v144
	ds_bpermute_b32 v137, v10, v129
	ds_bpermute_b32 v138, v10, v130
	ds_bpermute_b32 v139, v10, v131
	ds_bpermute_b32 v140, v10, v132
	ds_bpermute_b32 v141, v10, v133
	ds_bpermute_b32 v142, v10, v134
	ds_bpermute_b32 v143, v10, v135
	ds_bpermute_b32 v144, v10, v136
	s_waitcnt lgkmcnt(7)
	v_add_f32_e32 v129, v129, v137
	s_waitcnt lgkmcnt(6)
	v_add_f32_e32 v130, v130, v138
	s_waitcnt lgkmcnt(5)
	v_add_f32_e32 v131, v131, v139
	s_waitcnt lgkmcnt(4)
	v_add_f32_e32 v132, v132, v140
	s_waitcnt lgkmcnt(3)
	v_add_f32_e32 v133, v133, v141
	s_waitcnt lgkmcnt(2)
	v_add_f32_e32 v134, v134, v142
	s_waitcnt lgkmcnt(1)
	v_add_f32_e32 v135, v135, v143
	s_waitcnt lgkmcnt(0)
; __device__ __forceinline__ float bflo(unsigned w) { return __uint_as_float(w << 16); }
; __device__ __forceinline__ float bfhi(unsigned w) { return __uint_as_float(w & 0xffff0000u); }
; __device__ __forceinline__ unsigned pk2(float lo, float hi) { return pg8::cvt_pk_bf16(lo, hi); }
; __device__ __forceinline__ float siluf(float x) { return x * __builtin_amdgcn_rcpf(1.0f + __expf(-x)); }
; __device__ __forceinline__ void hgrn_post_phase(const float* oraw, const bf16* z, const float* onorm, bf16* oa, int gw, int NGW, int lane) {
;     ...
;         const float r = rsqrtf(wave_sum(o.x * o.x + o.y * o.y) * (1.0f / 128.0f) + EPS);
;         const unsigned gw2 = *(const unsigned*)(z + (size_t)row * ZP + C_HG + h * 128 + 2 * lane);
;         *(unsigned*)(oa + (size_t)row * 512 + h * 128 + 2 * lane) = pk2(o.x * r * g0 * siluf(bflo(gw2)), o.y * r * g1 * siluf(bfhi(gw2)));
	v_add_f32_e32 v136, v136, v144
	s_mov_b32 s16, s0
	s_mov_b32 s17, s1
	v_lshlrev_b32_e32 v12, 16, v121
	v_and_b32_e32 v13, 0xffff0000, v121
	v_fmamk_f32 v11, v129, 0x3c000000, v213
	v_cmp_gt_f32_e32 vcc, s83, v11
	v_mul_f32_e32 v16, 0x4b800000, v11
	s_nop 0
	v_cndmask_b32_e32 v11, v11, v16, vcc
	v_rsq_f32_e32 v11, v11
	s_nop 0
	v_mul_f32_e32 v16, 0x45800000, v11
	v_cndmask_b32_e32 v16, v11, v16, vcc
	v_mul_f32_e32 v11, 0xbfb8aa3b, v12
	v_exp_f32_e32 v11, v11
	v_pk_mul_f32 v[104:105], v[104:105], v[16:17] op_sel_hi:[1,0]
	v_add_f32_e32 v11, 1.0, v11
	v_rcp_f32_e32 v18, v11
	v_mul_f32_e32 v11, 0xbfb8aa3b, v13
	v_exp_f32_e32 v11, v11
	v_pk_mul_f32 v[104:105], v[4:5], v[104:105]
	v_add_f32_e32 v11, 1.0, v11
	v_rcp_f32_e32 v19, v11
	s_ashr_i32 s4, s16, 2
	s_ashr_i32 s5, s4, 31
	s_lshl_b64 s[4:5], s[4:5], 10
	s_add_u32 s4, s46, s4
	s_addc_u32 s5, s24, s5
	s_and_b32 s8, s17, 0x180
	s_lshl_b32 s8, s8, 1
	s_add_u32 s4, s4, s8
	s_addc_u32 s5, s5, 0
	v_pk_mul_f32 v[12:13], v[18:19], v[12:13]
	s_nop 0
	v_pk_mul_f32 v[12:13], v[12:13], v[104:105]
	s_nop 0
	v_cvt_pk_bf16_f32 v11, v12, v13
	global_store_dword v101, v11, s[4:5]
	s_add_i32 s16, s16, s12
	s_add_i32 s17, s17, s15
	v_lshlrev_b32_e32 v12, 16, v122
	v_and_b32_e32 v13, 0xffff0000, v122
	v_fmamk_f32 v11, v130, 0x3c000000, v213
	v_cmp_gt_f32_e32 vcc, s83, v11
	v_mul_f32_e32 v16, 0x4b800000, v11
	s_nop 0
	v_cndmask_b32_e32 v11, v11, v16, vcc
	v_rsq_f32_e32 v11, v11
	s_nop 0
	v_mul_f32_e32 v16, 0x45800000, v11
	v_cndmask_b32_e32 v16, v11, v16, vcc
	v_mul_f32_e32 v11, 0xbfb8aa3b, v12
	v_exp_f32_e32 v11, v11
	v_pk_mul_f32 v[106:107], v[106:107], v[16:17] op_sel_hi:[1,0]
	v_add_f32_e32 v11, 1.0, v11
	v_rcp_f32_e32 v18, v11
	v_mul_f32_e32 v11, 0xbfb8aa3b, v13
	v_exp_f32_e32 v11, v11
	v_pk_mul_f32 v[106:107], v[4:5], v[106:107]
	v_add_f32_e32 v11, 1.0, v11
	v_rcp_f32_e32 v19, v11
	s_ashr_i32 s4, s16, 2
	s_ashr_i32 s5, s4, 31
	s_lshl_b64 s[4:5], s[4:5], 10
	s_add_u32 s4, s46, s4
	s_addc_u32 s5, s24, s5
	s_and_b32 s8, s17, 0x180
	s_lshl_b32 s8, s8, 1
	s_add_u32 s4, s4, s8
	s_addc_u32 s5, s5, 0
	v_pk_mul_f32 v[12:13], v[18:19], v[12:13]
	s_nop 0
	v_pk_mul_f32 v[12:13], v[12:13], v[106:107]
	s_nop 0
	v_cvt_pk_bf16_f32 v11, v12, v13
	global_store_dword v101, v11, s[4:5]
	s_add_i32 s16, s16, s12
	s_add_i32 s17, s17, s15
	v_lshlrev_b32_e32 v12, 16, v123
	v_and_b32_e32 v13, 0xffff0000, v123
	v_fmamk_f32 v11, v131, 0x3c000000, v213
	v_cmp_gt_f32_e32 vcc, s83, v11
	v_mul_f32_e32 v16, 0x4b800000, v11
	s_nop 0
	v_cndmask_b32_e32 v11, v11, v16, vcc
	v_rsq_f32_e32 v11, v11
	s_nop 0
	v_mul_f32_e32 v16, 0x45800000, v11
	v_cndmask_b32_e32 v16, v11, v16, vcc
	v_mul_f32_e32 v11, 0xbfb8aa3b, v12
	v_exp_f32_e32 v11, v11
	v_pk_mul_f32 v[108:109], v[108:109], v[16:17] op_sel_hi:[1,0]
	v_add_f32_e32 v11, 1.0, v11
	v_rcp_f32_e32 v18, v11
	v_mul_f32_e32 v11, 0xbfb8aa3b, v13
	v_exp_f32_e32 v11, v11
	v_pk_mul_f32 v[108:109], v[4:5], v[108:109]
	v_add_f32_e32 v11, 1.0, v11
	v_rcp_f32_e32 v19, v11
	s_ashr_i32 s4, s16, 2
	s_ashr_i32 s5, s4, 31
	s_lshl_b64 s[4:5], s[4:5], 10
	s_add_u32 s4, s46, s4
	s_addc_u32 s5, s24, s5
	s_and_b32 s8, s17, 0x180
	s_lshl_b32 s8, s8, 1
	s_add_u32 s4, s4, s8
	s_addc_u32 s5, s5, 0
	v_pk_mul_f32 v[12:13], v[18:19], v[12:13]
	s_nop 0
	v_pk_mul_f32 v[12:13], v[12:13], v[108:109]
	s_nop 0
	v_cvt_pk_bf16_f32 v11, v12, v13
	global_store_dword v101, v11, s[4:5]
	s_add_i32 s16, s16, s12
	s_add_i32 s17, s17, s15
	v_lshlrev_b32_e32 v12, 16, v124
	v_and_b32_e32 v13, 0xffff0000, v124
	v_fmamk_f32 v11, v132, 0x3c000000, v213
	v_cmp_gt_f32_e32 vcc, s83, v11
	v_mul_f32_e32 v16, 0x4b800000, v11
	s_nop 0
	v_cndmask_b32_e32 v11, v11, v16, vcc
	v_rsq_f32_e32 v11, v11
	s_nop 0
	v_mul_f32_e32 v16, 0x45800000, v11
	v_cndmask_b32_e32 v16, v11, v16, vcc
	v_mul_f32_e32 v11, 0xbfb8aa3b, v12
	v_exp_f32_e32 v11, v11
	v_pk_mul_f32 v[110:111], v[110:111], v[16:17] op_sel_hi:[1,0]
	v_add_f32_e32 v11, 1.0, v11
	v_rcp_f32_e32 v18, v11
	v_mul_f32_e32 v11, 0xbfb8aa3b, v13
	v_exp_f32_e32 v11, v11
	v_pk_mul_f32 v[110:111], v[4:5], v[110:111]
	v_add_f32_e32 v11, 1.0, v11
	v_rcp_f32_e32 v19, v11
	s_ashr_i32 s4, s16, 2
	s_ashr_i32 s5, s4, 31
	s_lshl_b64 s[4:5], s[4:5], 10
	s_add_u32 s4, s46, s4
	s_addc_u32 s5, s24, s5
	s_and_b32 s8, s17, 0x180
	s_lshl_b32 s8, s8, 1
	s_add_u32 s4, s4, s8
	s_addc_u32 s5, s5, 0
	v_pk_mul_f32 v[12:13], v[18:19], v[12:13]
	s_nop 0
	v_pk_mul_f32 v[12:13], v[12:13], v[110:111]
	s_nop 0
	v_cvt_pk_bf16_f32 v11, v12, v13
	global_store_dword v101, v11, s[4:5]
	s_add_i32 s16, s16, s12
	s_add_i32 s17, s17, s15
	v_lshlrev_b32_e32 v12, 16, v125
; __device__ __forceinline__ float bflo(unsigned w) { return __uint_as_float(w << 16); }
; __device__ __forceinline__ float bfhi(unsigned w) { return __uint_as_float(w & 0xffff0000u); }
; __device__ __forceinline__ unsigned pk2(float lo, float hi) { return pg8::cvt_pk_bf16(lo, hi); }
; __device__ __forceinline__ float siluf(float x) { return x * __builtin_amdgcn_rcpf(1.0f + __expf(-x)); }
; __device__ __forceinline__ void hgrn_post_phase(const float* oraw, const bf16* z, const float* onorm, bf16* oa, int gw, int NGW, int lane) {
;     ...
;         const float r = rsqrtf(wave_sum(o.x * o.x + o.y * o.y) * (1.0f / 128.0f) + EPS);
;         const unsigned gw2 = *(const unsigned*)(z + (size_t)row * ZP + C_HG + h * 128 + 2 * lane);
;         *(unsigned*)(oa + (size_t)row * 512 + h * 128 + 2 * lane) = pk2(o.x * r * g0 * siluf(bflo(gw2)), o.y * r * g1 * siluf(bfhi(gw2)));
	v_and_b32_e32 v13, 0xffff0000, v125
	v_fmamk_f32 v11, v133, 0x3c000000, v213
	v_cmp_gt_f32_e32 vcc, s83, v11
	v_mul_f32_e32 v16, 0x4b800000, v11
	s_nop 0
	v_cndmask_b32_e32 v11, v11, v16, vcc
	v_rsq_f32_e32 v11, v11
	s_nop 0
	v_mul_f32_e32 v16, 0x45800000, v11
	v_cndmask_b32_e32 v16, v11, v16, vcc
	v_mul_f32_e32 v11, 0xbfb8aa3b, v12
	v_exp_f32_e32 v11, v11
	v_pk_mul_f32 v[112:113], v[112:113], v[16:17] op_sel_hi:[1,0]
	v_add_f32_e32 v11, 1.0, v11
	v_rcp_f32_e32 v18, v11
	v_mul_f32_e32 v11, 0xbfb8aa3b, v13
	v_exp_f32_e32 v11, v11
	v_pk_mul_f32 v[112:113], v[4:5], v[112:113]
	v_add_f32_e32 v11, 1.0, v11
	v_rcp_f32_e32 v19, v11
	s_ashr_i32 s4, s16, 2
	s_ashr_i32 s5, s4, 31
	s_lshl_b64 s[4:5], s[4:5], 10
	s_add_u32 s4, s46, s4
	s_addc_u32 s5, s24, s5
	s_and_b32 s8, s17, 0x180
	s_lshl_b32 s8, s8, 1
	s_add_u32 s4, s4, s8
	s_addc_u32 s5, s5, 0
	v_pk_mul_f32 v[12:13], v[18:19], v[12:13]
	s_nop 0
	v_pk_mul_f32 v[12:13], v[12:13], v[112:113]
	s_nop 0
	v_cvt_pk_bf16_f32 v11, v12, v13
	global_store_dword v101, v11, s[4:5]
	s_add_i32 s16, s16, s12
	s_add_i32 s17, s17, s15
	v_lshlrev_b32_e32 v12, 16, v126
	v_and_b32_e32 v13, 0xffff0000, v126
	v_fmamk_f32 v11, v134, 0x3c000000, v213
	v_cmp_gt_f32_e32 vcc, s83, v11
	v_mul_f32_e32 v16, 0x4b800000, v11
	s_nop 0
	v_cndmask_b32_e32 v11, v11, v16, vcc
	v_rsq_f32_e32 v11, v11
	s_nop 0
	v_mul_f32_e32 v16, 0x45800000, v11
	v_cndmask_b32_e32 v16, v11, v16, vcc
	v_mul_f32_e32 v11, 0xbfb8aa3b, v12
	v_exp_f32_e32 v11, v11
	v_pk_mul_f32 v[114:115], v[114:115], v[16:17] op_sel_hi:[1,0]
	v_add_f32_e32 v11, 1.0, v11
	v_rcp_f32_e32 v18, v11
	v_mul_f32_e32 v11, 0xbfb8aa3b, v13
	v_exp_f32_e32 v11, v11
	v_pk_mul_f32 v[114:115], v[4:5], v[114:115]
	v_add_f32_e32 v11, 1.0, v11
	v_rcp_f32_e32 v19, v11
	s_ashr_i32 s4, s16, 2
	s_ashr_i32 s5, s4, 31
	s_lshl_b64 s[4:5], s[4:5], 10
	s_add_u32 s4, s46, s4
	s_addc_u32 s5, s24, s5
	s_and_b32 s8, s17, 0x180
	s_lshl_b32 s8, s8, 1
	s_add_u32 s4, s4, s8
	s_addc_u32 s5, s5, 0
	v_pk_mul_f32 v[12:13], v[18:19], v[12:13]
	s_nop 0
	v_pk_mul_f32 v[12:13], v[12:13], v[114:115]
	s_nop 0
	v_cvt_pk_bf16_f32 v11, v12, v13
	global_store_dword v101, v11, s[4:5]
	s_add_i32 s16, s16, s12
	s_add_i32 s17, s17, s15
	v_lshlrev_b32_e32 v12, 16, v127
	v_and_b32_e32 v13, 0xffff0000, v127
	v_fmamk_f32 v11, v135, 0x3c000000, v213
	v_cmp_gt_f32_e32 vcc, s83, v11
	v_mul_f32_e32 v16, 0x4b800000, v11
	s_nop 0
	v_cndmask_b32_e32 v11, v11, v16, vcc
	v_rsq_f32_e32 v11, v11
	s_nop 0
	v_mul_f32_e32 v16, 0x45800000, v11
	v_cndmask_b32_e32 v16, v11, v16, vcc
	v_mul_f32_e32 v11, 0xbfb8aa3b, v12
	v_exp_f32_e32 v11, v11
	v_pk_mul_f32 v[116:117], v[116:117], v[16:17] op_sel_hi:[1,0]
	v_add_f32_e32 v11, 1.0, v11
	v_rcp_f32_e32 v18, v11
	v_mul_f32_e32 v11, 0xbfb8aa3b, v13
	v_exp_f32_e32 v11, v11
	v_pk_mul_f32 v[116:117], v[4:5], v[116:117]
	v_add_f32_e32 v11, 1.0, v11
	v_rcp_f32_e32 v19, v11
	s_ashr_i32 s4, s16, 2
	s_ashr_i32 s5, s4, 31
	s_lshl_b64 s[4:5], s[4:5], 10
	s_add_u32 s4, s46, s4
	s_addc_u32 s5, s24, s5
	s_and_b32 s8, s17, 0x180
	s_lshl_b32 s8, s8, 1
	s_add_u32 s4, s4, s8
	s_addc_u32 s5, s5, 0
	v_pk_mul_f32 v[12:13], v[18:19], v[12:13]
	s_nop 0
	v_pk_mul_f32 v[12:13], v[12:13], v[116:117]
	s_nop 0
	v_cvt_pk_bf16_f32 v11, v12, v13
	global_store_dword v101, v11, s[4:5]
	s_add_i32 s16, s16, s12
	s_add_i32 s17, s17, s15
	v_lshlrev_b32_e32 v12, 16, v128
	v_and_b32_e32 v13, 0xffff0000, v128
	v_fmamk_f32 v11, v136, 0x3c000000, v213
	v_cmp_gt_f32_e32 vcc, s83, v11
	v_mul_f32_e32 v16, 0x4b800000, v11
	s_nop 0
	v_cndmask_b32_e32 v11, v11, v16, vcc
	v_rsq_f32_e32 v11, v11
	s_nop 0
	v_mul_f32_e32 v16, 0x45800000, v11
	v_cndmask_b32_e32 v16, v11, v16, vcc
	v_mul_f32_e32 v11, 0xbfb8aa3b, v12
	v_exp_f32_e32 v11, v11
	v_pk_mul_f32 v[118:119], v[118:119], v[16:17] op_sel_hi:[1,0]
	v_add_f32_e32 v11, 1.0, v11
	v_rcp_f32_e32 v18, v11
	v_mul_f32_e32 v11, 0xbfb8aa3b, v13
	v_exp_f32_e32 v11, v11
	v_pk_mul_f32 v[118:119], v[4:5], v[118:119]
	v_add_f32_e32 v11, 1.0, v11
	v_rcp_f32_e32 v19, v11
	s_ashr_i32 s4, s16, 2
	s_ashr_i32 s5, s4, 31
	s_lshl_b64 s[4:5], s[4:5], 10
	s_add_u32 s4, s46, s4
	s_addc_u32 s5, s24, s5
	s_and_b32 s8, s17, 0x180
	s_lshl_b32 s8, s8, 1
	s_add_u32 s4, s4, s8
	s_addc_u32 s5, s5, 0
	v_pk_mul_f32 v[12:13], v[18:19], v[12:13]
	s_nop 0
	v_pk_mul_f32 v[12:13], v[12:13], v[118:119]
	s_nop 0
	v_cvt_pk_bf16_f32 v11, v12, v13
	global_store_dword v101, v11, s[4:5]
	s_add_i32 s16, s16, s12
	s_add_i32 s17, s17, s15
	s_mov_b32 s0, s16
	s_mov_b32 s1, s17
	s_branch .Lhp_check
.Lhp_tail:
	s_cmp_gt_i32 s0, 0xffff
	s_cbranch_scc1 .LBB0_795

;     __device__ __forceinline__ void operator()(const f32x4 (&acc)[2][2][4][2], const Unit& u, int wr, int wc, int fr, int fq) const {
;         const int row0 = u.pm * 256 + wr * 64 + fr, col0 = u.pn * 256 + wc * 32 + 4 * fq, b = u.pm >> 3;
;         f32x4 gv[2][2];
; #pragma unroll
;         for (int bj = 0; bj < 2; ++bj)
; #pragma unroll
;             for (int n = 0; n < 2; ++n) gv[bj][n] = *(const f32x4*)(gate + (size_t)b * MODW + col0 + bj * 128 + n * 16) * scale;
; #pragma unroll
;         for (int ai = 0; ai < 2; ++ai)
; #pragma unroll
;             for (int m = 0; m < 4; ++m) { const size_t off = (size_t)(row0 + ai * 128 + m * 16) * D + col0;
; #pragma unroll
;                 for (int bj = 0; bj < 2; ++bj)
; #pragma unroll
;                     for (int n = 0; n < 2; ++n) { const f32x4 hv = *(const f32x4*)(hin + off + bj * 128 + n * 16);
;                         *(f32x4*)(hout + off + bj * 128 + n * 16) = hv + gv[bj][n] * acc[ai][bj][m][n]; } }
;     }
.LBB0_1103:
	s_ashr_i32 s4, s38, 3
	s_mul_hi_i32 s5, s4, 0x12000
	s_mul_i32 s4, s4, 0x12000
	s_add_u32 s4, s31, s4
	s_addc_u32 s5, s34, s5
	v_lshl_or_b32 v158, s39, 8, v161
	v_lshlrev_b32_e32 v159, 2, v158
	global_load_dwordx4 v[52:55], v159, s[4:5]
	global_load_dwordx4 v[88:91], v159, s[4:5] offset:64
	global_load_dwordx4 v[100:103], v159, s[4:5] offset:512
	global_load_dwordx4 v[112:115], v159, s[4:5] offset:576
	v_lshl_add_u32 v172, s38, 8, v1
	v_lshlrev_b32_e32 v173, 13, v172
	v_add_u32_e32 v173, v173, v159
	v_mov_b32_e32 v210, v173
	global_load_dwordx4 v[154:157], v210, s[54:55]
	global_load_dwordx4 v[164:167], v210, s[54:55] offset:64
	global_load_dwordx4 v[168:171], v210, s[54:55] offset:512
	global_load_dwordx4 v[186:189], v210, s[54:55] offset:576
	v_add_u32_e32 v211, 0x20000, v173
	global_load_dwordx4 v[190:193], v211, s[54:55]
	global_load_dwordx4 v[194:197], v211, s[54:55] offset:64
	global_load_dwordx4 v[198:201], v211, s[54:55] offset:512
	global_load_dwordx4 v[202:205], v211, s[54:55] offset:576
	v_add_u32_e32 v214, 0x40000, v173
	global_load_dwordx4 v[206:209], v214, s[54:55]
	global_load_dwordx4 v[236:239], v214, s[54:55] offset:64
	global_load_dwordx4 v[240:243], v214, s[54:55] offset:512
	global_load_dwordx4 v[244:247], v214, s[54:55] offset:576
	s_ashr_i32 s4, s38, 3
	s_mul_hi_i32 s5, s4, 0x12000
	s_mul_i32 s4, s4, 0x12000
	s_add_u32 s4, s31, s4
	s_addc_u32 s5, s34, s5
	s_mov_b64 s[4:5], 0x100000
	v_readlane_b32 s46, v255, 23
	s_mov_b32 s4, 0x100000
	s_mov_b64 s[4:5], 0x120000
	s_mov_b32 s4, 0x120000
	s_mov_b64 s[4:5], 0x140000
	s_mov_b32 s4, 0x140000
	s_mov_b64 s[4:5], 0x160000
	s_mov_b32 s4, 0x160000
	s_mov_b64 s[4:5], -1
	s_andn2_b64 vcc, exec, s[8:9]
	s_waitcnt vmcnt(12)
	s_waitcnt vmcnt(8)
	v_pk_fma_f32 v[146:147], v[146:147], v[54:55], v[156:157]
	v_pk_fma_f32 v[144:145], v[144:145], v[52:53], v[154:155]
	v_pk_fma_f32 v[142:143], v[142:143], v[90:91], v[166:167]
	v_pk_fma_f32 v[140:141], v[140:141], v[88:89], v[164:165]
	v_pk_fma_f32 v[138:139], v[138:139], v[102:103], v[170:171]
	v_pk_fma_f32 v[136:137], v[136:137], v[100:101], v[168:169]
	v_pk_fma_f32 v[134:135], v[134:135], v[114:115], v[188:189]
	v_pk_fma_f32 v[132:133], v[132:133], v[112:113], v[186:187]
	global_store_dwordx4 v210, v[144:147], s[54:55]
	global_store_dwordx4 v210, v[140:143], s[54:55] offset:64
	global_store_dwordx4 v210, v[136:139], s[54:55] offset:512
	global_store_dwordx4 v210, v[132:135], s[54:55] offset:576
	v_add_u32_e32 v210, 0x60000, v173
	global_load_dwordx4 v[154:157], v210, s[54:55]
	global_load_dwordx4 v[164:167], v210, s[54:55] offset:64
	global_load_dwordx4 v[168:171], v210, s[54:55] offset:512
	global_load_dwordx4 v[186:189], v210, s[54:55] offset:576
	s_waitcnt vmcnt(12)
	v_pk_fma_f32 v[130:131], v[130:131], v[54:55], v[192:193]
	v_pk_fma_f32 v[128:129], v[128:129], v[52:53], v[190:191]
	v_pk_fma_f32 v[126:127], v[126:127], v[90:91], v[196:197]
	v_pk_fma_f32 v[124:125], v[124:125], v[88:89], v[194:195]
	v_pk_fma_f32 v[122:123], v[122:123], v[102:103], v[200:201]
	v_pk_fma_f32 v[120:121], v[120:121], v[100:101], v[198:199]
	v_pk_fma_f32 v[118:119], v[118:119], v[114:115], v[204:205]
	v_pk_fma_f32 v[116:117], v[116:117], v[112:113], v[202:203]
	global_store_dwordx4 v211, v[128:131], s[54:55]
	global_store_dwordx4 v211, v[124:127], s[54:55] offset:64
	global_store_dwordx4 v211, v[120:123], s[54:55] offset:512
	global_store_dwordx4 v211, v[116:119], s[54:55] offset:576
	v_add_u32_e32 v211, 0x100000, v173
	global_load_dwordx4 v[190:193], v211, s[54:55]
	global_load_dwordx4 v[194:197], v211, s[54:55] offset:64
	global_load_dwordx4 v[198:201], v211, s[54:55] offset:512
	global_load_dwordx4 v[202:205], v211, s[54:55] offset:576
	s_waitcnt vmcnt(16)
	v_pk_fma_f32 v[110:111], v[110:111], v[54:55], v[208:209]
	v_pk_fma_f32 v[108:109], v[108:109], v[52:53], v[206:207]
	v_pk_fma_f32 v[106:107], v[106:107], v[90:91], v[238:239]
	v_pk_fma_f32 v[104:105], v[104:105], v[88:89], v[236:237]
	v_pk_fma_f32 v[98:99], v[98:99], v[102:103], v[242:243]
	v_pk_fma_f32 v[96:97], v[96:97], v[100:101], v[240:241]
	v_pk_fma_f32 v[94:95], v[94:95], v[114:115], v[246:247]
	v_pk_fma_f32 v[92:93], v[92:93], v[112:113], v[244:245]
	global_store_dwordx4 v214, v[108:111], s[54:55]
	global_store_dwordx4 v214, v[104:107], s[54:55] offset:64
	global_store_dwordx4 v214, v[96:99], s[54:55] offset:512
	global_store_dwordx4 v214, v[92:95], s[54:55] offset:576
	v_add_u32_e32 v214, 0x120000, v173
	global_load_dwordx4 v[206:209], v214, s[54:55]
	global_load_dwordx4 v[236:239], v214, s[54:55] offset:64
	global_load_dwordx4 v[240:243], v214, s[54:55] offset:512
	global_load_dwordx4 v[244:247], v214, s[54:55] offset:576
	s_waitcnt vmcnt(16)
;     __device__ __forceinline__ void operator()(const f32x4 (&acc)[2][2][4][2], const Unit& u, int wr, int wc, int fr, int fq) const {
;     ...
;         for (int ai = 0; ai < 2; ++ai)
; #pragma unroll
;             for (int m = 0; m < 4; ++m) { const size_t off = (size_t)(row0 + ai * 128 + m * 16) * D + col0;
; #pragma unroll
;                 for (int bj = 0; bj < 2; ++bj)
; #pragma unroll
;                     for (int n = 0; n < 2; ++n) { const f32x4 hv = *(const f32x4*)(hin + off + bj * 128 + n * 16);
;                         *(f32x4*)(hout + off + bj * 128 + n * 16) = hv + gv[bj][n] * acc[ai][bj][m][n]; } }
;     }
	v_pk_fma_f32 v[86:87], v[86:87], v[54:55], v[156:157]
	v_pk_fma_f32 v[84:85], v[84:85], v[52:53], v[154:155]
	v_pk_fma_f32 v[82:83], v[82:83], v[90:91], v[166:167]
	v_pk_fma_f32 v[80:81], v[80:81], v[88:89], v[164:165]
	v_pk_fma_f32 v[78:79], v[78:79], v[102:103], v[170:171]
	v_pk_fma_f32 v[76:77], v[76:77], v[100:101], v[168:169]
	v_pk_fma_f32 v[74:75], v[74:75], v[114:115], v[188:189]
	v_pk_fma_f32 v[72:73], v[72:73], v[112:113], v[186:187]
	global_store_dwordx4 v210, v[84:87], s[54:55]
	global_store_dwordx4 v210, v[80:83], s[54:55] offset:64
	global_store_dwordx4 v210, v[76:79], s[54:55] offset:512
	global_store_dwordx4 v210, v[72:75], s[54:55] offset:576
	v_add_u32_e32 v210, 0x140000, v173
	global_load_dwordx4 v[154:157], v210, s[54:55]
	global_load_dwordx4 v[164:167], v210, s[54:55] offset:64
	global_load_dwordx4 v[168:171], v210, s[54:55] offset:512
	global_load_dwordx4 v[186:189], v210, s[54:55] offset:576
	s_waitcnt vmcnt(16)
	v_pk_fma_f32 v[70:71], v[70:71], v[54:55], v[192:193]
	v_pk_fma_f32 v[68:69], v[68:69], v[52:53], v[190:191]
	v_pk_fma_f32 v[66:67], v[66:67], v[90:91], v[196:197]
	v_pk_fma_f32 v[64:65], v[64:65], v[88:89], v[194:195]
	v_pk_fma_f32 v[62:63], v[62:63], v[102:103], v[200:201]
	v_pk_fma_f32 v[60:61], v[60:61], v[100:101], v[198:199]
	v_pk_fma_f32 v[58:59], v[58:59], v[114:115], v[204:205]
	v_pk_fma_f32 v[56:57], v[56:57], v[112:113], v[202:203]
	global_store_dwordx4 v211, v[68:71], s[54:55]
	global_store_dwordx4 v211, v[64:67], s[54:55] offset:64
	global_store_dwordx4 v211, v[60:63], s[54:55] offset:512
	global_store_dwordx4 v211, v[56:59], s[54:55] offset:576
	v_add_u32_e32 v211, 0x160000, v173
	global_load_dwordx4 v[190:193], v211, s[54:55]
	global_load_dwordx4 v[194:197], v211, s[54:55] offset:64
	global_load_dwordx4 v[198:201], v211, s[54:55] offset:512
	global_load_dwordx4 v[202:205], v211, s[54:55] offset:576
	s_waitcnt vmcnt(16)
	v_pk_fma_f32 v[50:51], v[50:51], v[54:55], v[208:209]
	v_pk_fma_f32 v[48:49], v[48:49], v[52:53], v[206:207]
	v_pk_fma_f32 v[46:47], v[46:47], v[90:91], v[238:239]
	v_pk_fma_f32 v[44:45], v[44:45], v[88:89], v[236:237]
	v_pk_fma_f32 v[42:43], v[42:43], v[102:103], v[242:243]
	v_pk_fma_f32 v[40:41], v[40:41], v[100:101], v[240:241]
	v_pk_fma_f32 v[38:39], v[38:39], v[114:115], v[246:247]
	v_pk_fma_f32 v[36:37], v[36:37], v[112:113], v[244:245]
	global_store_dwordx4 v214, v[48:51], s[54:55]
	global_store_dwordx4 v214, v[44:47], s[54:55] offset:64
	global_store_dwordx4 v214, v[40:43], s[54:55] offset:512
	global_store_dwordx4 v214, v[36:39], s[54:55] offset:576
	s_waitcnt vmcnt(12)
	v_pk_fma_f32 v[34:35], v[34:35], v[54:55], v[156:157]
	v_pk_fma_f32 v[32:33], v[32:33], v[52:53], v[154:155]
	v_pk_fma_f32 v[30:31], v[30:31], v[90:91], v[166:167]
	v_pk_fma_f32 v[28:29], v[28:29], v[88:89], v[164:165]
	v_pk_fma_f32 v[26:27], v[26:27], v[102:103], v[170:171]
	v_pk_fma_f32 v[24:25], v[24:25], v[100:101], v[168:169]
	v_pk_fma_f32 v[22:23], v[22:23], v[114:115], v[188:189]
	v_pk_fma_f32 v[20:21], v[20:21], v[112:113], v[186:187]
	global_store_dwordx4 v210, v[32:35], s[54:55]
	global_store_dwordx4 v210, v[28:31], s[54:55] offset:64
	global_store_dwordx4 v210, v[24:27], s[54:55] offset:512
	global_store_dwordx4 v210, v[20:23], s[54:55] offset:576
	s_waitcnt vmcnt(8)
	v_pk_fma_f32 v[18:19], v[18:19], v[54:55], v[192:193]
	v_pk_fma_f32 v[16:17], v[16:17], v[52:53], v[190:191]
	v_pk_fma_f32 v[14:15], v[14:15], v[90:91], v[196:197]
	v_pk_fma_f32 v[12:13], v[12:13], v[88:89], v[194:195]
	v_pk_fma_f32 v[10:11], v[10:11], v[102:103], v[200:201]
	v_pk_fma_f32 v[8:9], v[8:9], v[100:101], v[198:199]
	v_pk_fma_f32 v[6:7], v[6:7], v[114:115], v[204:205]
	v_pk_fma_f32 v[4:5], v[4:5], v[112:113], v[202:203]
	global_store_dwordx4 v211, v[16:19], s[54:55]
	global_store_dwordx4 v211, v[12:15], s[54:55] offset:64
	global_store_dwordx4 v211, v[8:11], s[54:55] offset:512
	global_store_dwordx4 v211, v[4:7], s[54:55] offset:576
	s_cbranch_vccnz .LBB0_1092
	s_andn2_b64 vcc, exec, s[6:7]
	s_cbranch_vccnz .LBB0_1091
	s_barrier
	s_branch .LBB0_1091

;     __device__ __forceinline__ void operator()(const f32x4 (&acc)[2][2][4][2], const Unit& u, int wr, int wc, int fr, int fq) const {
;         const int row0 = u.pm * 256 + wr * 64 + fr, col0 = u.pn * 256 + wc * 32 + 4 * fq, b = u.pm >> 3;
;         f32x4 gv[2][2];
; #pragma unroll
;         for (int bj = 0; bj < 2; ++bj)
; #pragma unroll
;             for (int n = 0; n < 2; ++n) gv[bj][n] = *(const f32x4*)(gate + (size_t)b * MODW + col0 + bj * 128 + n * 16) * scale;
; #pragma unroll
;         for (int ai = 0; ai < 2; ++ai)
; #pragma unroll
;             for (int m = 0; m < 4; ++m) { const size_t off = (size_t)(row0 + ai * 128 + m * 16) * D + col0;
; #pragma unroll
;                 for (int bj = 0; bj < 2; ++bj)
; #pragma unroll
;                     for (int n = 0; n < 2; ++n) { const f32x4 hv = *(const f32x4*)(hin + off + bj * 128 + n * 16);
;                         *(f32x4*)(hout + off + bj * 128 + n * 16) = hv + gv[bj][n] * acc[ai][bj][m][n]; } }
;     }
.LBB0_1304:
	s_ashr_i32 s14, s36, 3
	s_mul_hi_i32 s15, s14, 0x12000
	s_mul_i32 s14, s14, 0x12000
	s_add_u32 s14, s27, s14
	s_addc_u32 s15, s28, s15
	v_lshl_or_b32 v158, s37, 8, v161
	v_lshlrev_b32_e32 v159, 2, v158
	global_load_dwordx4 v[138:141], v159, s[14:15]
	global_load_dwordx4 v[142:145], v159, s[14:15] offset:64
	global_load_dwordx4 v[146:149], v159, s[14:15] offset:512
	global_load_dwordx4 v[150:153], v159, s[14:15] offset:576
	v_lshl_add_u32 v172, s36, 8, v1
	v_lshlrev_b32_e32 v173, 13, v172
	v_add_u32_e32 v173, v173, v159
	v_mov_b32_e32 v210, v173
	global_load_dwordx4 v[154:157], v210, s[54:55]
	global_load_dwordx4 v[164:167], v210, s[54:55] offset:64
	global_load_dwordx4 v[168:171], v210, s[54:55] offset:512
	global_load_dwordx4 v[186:189], v210, s[54:55] offset:576
	v_add_u32_e32 v211, 0x20000, v173
	global_load_dwordx4 v[190:193], v211, s[54:55]
	global_load_dwordx4 v[194:197], v211, s[54:55] offset:64
	global_load_dwordx4 v[198:201], v211, s[54:55] offset:512
	global_load_dwordx4 v[202:205], v211, s[54:55] offset:576
	v_add_u32_e32 v214, 0x40000, v173
	global_load_dwordx4 v[206:209], v214, s[54:55]
	global_load_dwordx4 v[236:239], v214, s[54:55] offset:64
	global_load_dwordx4 v[240:243], v214, s[54:55] offset:512
	global_load_dwordx4 v[244:247], v214, s[54:55] offset:576
	s_ashr_i32 s14, s36, 3
	s_mul_hi_i32 s15, s14, 0x12000
	s_mul_i32 s14, s14, 0x12000
	s_add_u32 s14, s27, s14
	s_addc_u32 s15, s28, s15
	s_mov_b64 s[14:15], 0x100000
	s_mov_b32 s14, 0x100000
	s_mov_b64 s[14:15], 0x120000
	s_mov_b32 s14, 0x120000
	s_mov_b64 s[14:15], 0x140000
	s_mov_b32 s14, 0x140000
	s_mov_b64 s[14:15], 0x160000
	s_mov_b32 s14, 0x160000
	s_mov_b64 s[14:15], -1
	s_and_b64 vcc, exec, s[4:5]
	s_waitcnt vmcnt(12)
	v_pk_mul_f32 v[140:141], v[140:141], 0.5 op_sel_hi:[1,0]
	v_pk_mul_f32 v[138:139], v[138:139], 0.5 op_sel_hi:[1,0]
	v_pk_mul_f32 v[144:145], v[144:145], 0.5 op_sel_hi:[1,0]
	v_pk_mul_f32 v[142:143], v[142:143], 0.5 op_sel_hi:[1,0]
	v_pk_mul_f32 v[148:149], v[148:149], 0.5 op_sel_hi:[1,0]
	v_pk_mul_f32 v[146:147], v[146:147], 0.5 op_sel_hi:[1,0]
	v_pk_mul_f32 v[152:153], v[152:153], 0.5 op_sel_hi:[1,0]
	v_pk_mul_f32 v[150:151], v[150:151], 0.5 op_sel_hi:[1,0]
	s_waitcnt vmcnt(8)
	v_pk_fma_f32 v[130:131], v[130:131], v[140:141], v[156:157]
	v_pk_fma_f32 v[128:129], v[128:129], v[138:139], v[154:155]
	v_pk_fma_f32 v[126:127], v[126:127], v[144:145], v[166:167]
	v_pk_fma_f32 v[124:125], v[124:125], v[142:143], v[164:165]
	v_pk_fma_f32 v[122:123], v[122:123], v[148:149], v[170:171]
	v_pk_fma_f32 v[120:121], v[120:121], v[146:147], v[168:169]
	v_pk_fma_f32 v[118:119], v[118:119], v[152:153], v[188:189]
	v_pk_fma_f32 v[116:117], v[116:117], v[150:151], v[186:187]
	global_store_dwordx4 v210, v[128:131], s[54:55]
	global_store_dwordx4 v210, v[124:127], s[54:55] offset:64
	global_store_dwordx4 v210, v[120:123], s[54:55] offset:512
	global_store_dwordx4 v210, v[116:119], s[54:55] offset:576
	v_add_u32_e32 v210, 0x60000, v173
	global_load_dwordx4 v[154:157], v210, s[54:55]
	global_load_dwordx4 v[164:167], v210, s[54:55] offset:64
	global_load_dwordx4 v[168:171], v210, s[54:55] offset:512
	global_load_dwordx4 v[186:189], v210, s[54:55] offset:576
	s_waitcnt vmcnt(12)
	v_pk_fma_f32 v[114:115], v[114:115], v[140:141], v[192:193]
	v_pk_fma_f32 v[112:113], v[112:113], v[138:139], v[190:191]
	v_pk_fma_f32 v[110:111], v[110:111], v[144:145], v[196:197]
	v_pk_fma_f32 v[108:109], v[108:109], v[142:143], v[194:195]
	v_pk_fma_f32 v[106:107], v[106:107], v[148:149], v[200:201]
	v_pk_fma_f32 v[104:105], v[104:105], v[146:147], v[198:199]
	v_pk_fma_f32 v[102:103], v[102:103], v[152:153], v[204:205]
	v_pk_fma_f32 v[100:101], v[100:101], v[150:151], v[202:203]
	global_store_dwordx4 v211, v[112:115], s[54:55]
	global_store_dwordx4 v211, v[108:111], s[54:55] offset:64
	global_store_dwordx4 v211, v[104:107], s[54:55] offset:512
	global_store_dwordx4 v211, v[100:103], s[54:55] offset:576
	v_add_u32_e32 v211, 0x100000, v173
	global_load_dwordx4 v[190:193], v211, s[54:55]
	global_load_dwordx4 v[194:197], v211, s[54:55] offset:64
	global_load_dwordx4 v[198:201], v211, s[54:55] offset:512
	global_load_dwordx4 v[202:205], v211, s[54:55] offset:576
	s_waitcnt vmcnt(16)
;     __device__ __forceinline__ void operator()(const f32x4 (&acc)[2][2][4][2], const Unit& u, int wr, int wc, int fr, int fq) const {
;     ...
;         for (int ai = 0; ai < 2; ++ai)
; #pragma unroll
;             for (int m = 0; m < 4; ++m) { const size_t off = (size_t)(row0 + ai * 128 + m * 16) * D + col0;
; #pragma unroll
;                 for (int bj = 0; bj < 2; ++bj)
; #pragma unroll
;                     for (int n = 0; n < 2; ++n) { const f32x4 hv = *(const f32x4*)(hin + off + bj * 128 + n * 16);
;                         *(f32x4*)(hout + off + bj * 128 + n * 16) = hv + gv[bj][n] * acc[ai][bj][m][n]; } }
;     }
	v_pk_fma_f32 v[98:99], v[98:99], v[140:141], v[208:209]
	v_pk_fma_f32 v[96:97], v[96:97], v[138:139], v[206:207]
	v_pk_fma_f32 v[94:95], v[94:95], v[144:145], v[238:239]
	v_pk_fma_f32 v[92:93], v[92:93], v[142:143], v[236:237]
	v_pk_fma_f32 v[90:91], v[90:91], v[148:149], v[242:243]
	v_pk_fma_f32 v[88:89], v[88:89], v[146:147], v[240:241]
	v_pk_fma_f32 v[86:87], v[86:87], v[152:153], v[246:247]
	v_pk_fma_f32 v[84:85], v[84:85], v[150:151], v[244:245]
	global_store_dwordx4 v214, v[96:99], s[54:55]
	global_store_dwordx4 v214, v[92:95], s[54:55] offset:64
	global_store_dwordx4 v214, v[88:91], s[54:55] offset:512
	global_store_dwordx4 v214, v[84:87], s[54:55] offset:576
	v_add_u32_e32 v214, 0x120000, v173
	global_load_dwordx4 v[206:209], v214, s[54:55]
	global_load_dwordx4 v[236:239], v214, s[54:55] offset:64
	global_load_dwordx4 v[240:243], v214, s[54:55] offset:512
	global_load_dwordx4 v[244:247], v214, s[54:55] offset:576
	s_waitcnt vmcnt(16)
	v_pk_fma_f32 v[82:83], v[82:83], v[140:141], v[156:157]
	v_pk_fma_f32 v[80:81], v[80:81], v[138:139], v[154:155]
	v_pk_fma_f32 v[78:79], v[78:79], v[144:145], v[166:167]
	v_pk_fma_f32 v[76:77], v[76:77], v[142:143], v[164:165]
	v_pk_fma_f32 v[74:75], v[74:75], v[148:149], v[170:171]
	v_pk_fma_f32 v[72:73], v[72:73], v[146:147], v[168:169]
	v_pk_fma_f32 v[70:71], v[70:71], v[152:153], v[188:189]
	v_pk_fma_f32 v[68:69], v[68:69], v[150:151], v[186:187]
	global_store_dwordx4 v210, v[80:83], s[54:55]
	global_store_dwordx4 v210, v[76:79], s[54:55] offset:64
	global_store_dwordx4 v210, v[72:75], s[54:55] offset:512
	global_store_dwordx4 v210, v[68:71], s[54:55] offset:576
	v_add_u32_e32 v210, 0x140000, v173
	global_load_dwordx4 v[154:157], v210, s[54:55]
	global_load_dwordx4 v[164:167], v210, s[54:55] offset:64
	global_load_dwordx4 v[168:171], v210, s[54:55] offset:512
	global_load_dwordx4 v[186:189], v210, s[54:55] offset:576
	s_waitcnt vmcnt(16)
	v_pk_fma_f32 v[66:67], v[66:67], v[140:141], v[192:193]
	v_pk_fma_f32 v[64:65], v[64:65], v[138:139], v[190:191]
	v_pk_fma_f32 v[62:63], v[62:63], v[144:145], v[196:197]
	v_pk_fma_f32 v[60:61], v[60:61], v[142:143], v[194:195]
	v_pk_fma_f32 v[58:59], v[58:59], v[148:149], v[200:201]
	v_pk_fma_f32 v[56:57], v[56:57], v[146:147], v[198:199]
	v_pk_fma_f32 v[54:55], v[54:55], v[152:153], v[204:205]
	v_pk_fma_f32 v[52:53], v[52:53], v[150:151], v[202:203]
	global_store_dwordx4 v211, v[64:67], s[54:55]
	global_store_dwordx4 v211, v[60:63], s[54:55] offset:64
	global_store_dwordx4 v211, v[56:59], s[54:55] offset:512
	global_store_dwordx4 v211, v[52:55], s[54:55] offset:576
	v_add_u32_e32 v211, 0x160000, v173
	global_load_dwordx4 v[190:193], v211, s[54:55]
	global_load_dwordx4 v[194:197], v211, s[54:55] offset:64
	global_load_dwordx4 v[198:201], v211, s[54:55] offset:512
	global_load_dwordx4 v[202:205], v211, s[54:55] offset:576
	s_waitcnt vmcnt(16)
	v_pk_fma_f32 v[50:51], v[50:51], v[140:141], v[208:209]
	v_pk_fma_f32 v[48:49], v[48:49], v[138:139], v[206:207]
	v_pk_fma_f32 v[46:47], v[46:47], v[144:145], v[238:239]
	v_pk_fma_f32 v[44:45], v[44:45], v[142:143], v[236:237]
	v_pk_fma_f32 v[42:43], v[42:43], v[148:149], v[242:243]
	v_pk_fma_f32 v[40:41], v[40:41], v[146:147], v[240:241]
	v_pk_fma_f32 v[38:39], v[38:39], v[152:153], v[246:247]
	v_pk_fma_f32 v[36:37], v[36:37], v[150:151], v[244:245]
	global_store_dwordx4 v214, v[48:51], s[54:55]
	global_store_dwordx4 v214, v[44:47], s[54:55] offset:64
	global_store_dwordx4 v214, v[40:43], s[54:55] offset:512
	global_store_dwordx4 v214, v[36:39], s[54:55] offset:576
	s_waitcnt vmcnt(12)
	v_pk_fma_f32 v[34:35], v[34:35], v[140:141], v[156:157]
	v_pk_fma_f32 v[32:33], v[32:33], v[138:139], v[154:155]
	v_pk_fma_f32 v[30:31], v[30:31], v[144:145], v[166:167]
	v_pk_fma_f32 v[28:29], v[28:29], v[142:143], v[164:165]
	v_pk_fma_f32 v[26:27], v[26:27], v[148:149], v[170:171]
	v_pk_fma_f32 v[24:25], v[24:25], v[146:147], v[168:169]
	v_pk_fma_f32 v[22:23], v[22:23], v[152:153], v[188:189]
	v_pk_fma_f32 v[20:21], v[20:21], v[150:151], v[186:187]
	global_store_dwordx4 v210, v[32:35], s[54:55]
	global_store_dwordx4 v210, v[28:31], s[54:55] offset:64
	global_store_dwordx4 v210, v[24:27], s[54:55] offset:512
	global_store_dwordx4 v210, v[20:23], s[54:55] offset:576
	s_waitcnt vmcnt(8)
	v_pk_fma_f32 v[18:19], v[18:19], v[140:141], v[192:193]
	v_pk_fma_f32 v[16:17], v[16:17], v[138:139], v[190:191]
	v_pk_fma_f32 v[14:15], v[14:15], v[144:145], v[196:197]
	v_pk_fma_f32 v[12:13], v[12:13], v[142:143], v[194:195]
	v_pk_fma_f32 v[10:11], v[10:11], v[148:149], v[200:201]
	v_pk_fma_f32 v[8:9], v[8:9], v[146:147], v[198:199]
	v_pk_fma_f32 v[6:7], v[6:7], v[152:153], v[204:205]
	v_pk_fma_f32 v[4:5], v[4:5], v[150:151], v[202:203]
	global_store_dwordx4 v211, v[16:19], s[54:55]
	global_store_dwordx4 v211, v[12:15], s[54:55] offset:64
	global_store_dwordx4 v211, v[8:11], s[54:55] offset:512
	global_store_dwordx4 v211, v[4:7], s[54:55] offset:576
	s_cbranch_vccnz .LBB0_1289
	s_andn2_b64 vcc, exec, s[8:9]
	s_cbranch_vccnz .LBB0_1288
	s_barrier
	s_branch .LBB0_1288
